# v41 with MFMA-block priority 2 instead of 1
# baseline (speedup 1.0000x reference)
.LBB0_159:
	s_add_u32 s0, s22, 0xfff80080
	s_addc_u32 s1, s23, -1
	s_add_i32 s51, 0, 0x10000
	s_cmp_eq_u32 s50, 28
	s_cselect_b32 s27, s15, s1
	s_cselect_b32 s26, s46, s0
	v_add_u32_e32 v140, s51, v143
	s_cselect_b32 s25, s13, s49
	s_cselect_b32 s24, s47, s48
	s_add_i32 s0, 0, 0x14000
	ds_read_b128 v[146:149], v140
	ds_read_b128 v[150:153], v140 offset:1024
	ds_read_b128 v[154:157], v140 offset:2048
	ds_read_b128 v[158:161], v140 offset:3072
	v_add_u32_e32 v140, s0, v143
	ds_read_b128 v[162:165], v140
	ds_read_b128 v[166:169], v140 offset:1024
	ds_read_b128 v[170:173], v140 offset:2048
	ds_read_b128 v[174:177], v140 offset:3072
	v_lshl_add_u64 v[140:141], s[22:23], 0, v[136:137]
	s_add_i32 m0, s35, 0xc000
	ds_read_b128 v[178:181], v144
	ds_read_b128 v[182:185], v144 offset:1024
	ds_read_b128 v[192:195], v144 offset:2048
	ds_read_b128 v[196:199], v144 offset:3072
	ds_read_b128 v[200:203], v144 offset:4096
	ds_read_b128 v[204:207], v144 offset:5120
	ds_read_b128 v[208:211], v144 offset:6144
	ds_read_b128 v[212:215], v144 offset:7168
	global_load_lds_dwordx4 v[140:141], off
	v_lshl_add_u64 v[140:141], s[22:23], 0, v[138:139]
	s_add_i32 m0, s35, 0xe000
	s_nop 0
	global_load_lds_dwordx4 v[140:141], off
	s_waitcnt vmcnt(8)
	s_waitcnt lgkmcnt(0)
	s_setprio 2
	s_barrier

	v_mfma_f32_16x16x32_bf16 v[126:129], v[146:149], v[178:181], v[126:129]
	v_mfma_f32_16x16x32_bf16 v[118:121], v[154:157], v[178:181], v[118:121]
	v_mfma_f32_16x16x32_bf16 v[110:113], v[146:149], v[192:195], v[110:113]
	v_mfma_f32_16x16x32_bf16 v[102:105], v[154:157], v[192:195], v[102:105]
	v_mfma_f32_16x16x32_bf16 v[94:97], v[146:149], v[200:203], v[94:97]
	v_mfma_f32_16x16x32_bf16 v[86:89], v[154:157], v[200:203], v[86:89]
	v_mfma_f32_16x16x32_bf16 v[78:81], v[146:149], v[208:211], v[78:81]
	v_mfma_f32_16x16x32_bf16 v[70:73], v[154:157], v[208:211], v[70:73]
	v_mfma_f32_16x16x32_bf16 v[126:129], v[150:153], v[182:185], v[126:129]
	v_mfma_f32_16x16x32_bf16 v[118:121], v[158:161], v[182:185], v[118:121]
	v_mfma_f32_16x16x32_bf16 v[110:113], v[150:153], v[196:199], v[110:113]
	v_mfma_f32_16x16x32_bf16 v[102:105], v[158:161], v[196:199], v[102:105]
	v_mfma_f32_16x16x32_bf16 v[94:97], v[150:153], v[204:207], v[94:97]
	v_mfma_f32_16x16x32_bf16 v[86:89], v[158:161], v[204:207], v[86:89]
	v_mfma_f32_16x16x32_bf16 v[78:81], v[150:153], v[212:215], v[78:81]
	v_mfma_f32_16x16x32_bf16 v[70:73], v[158:161], v[212:215], v[70:73]


	v_mfma_f32_16x16x32_bf16 v[122:125], v[162:165], v[178:181], v[122:125]
	v_mfma_f32_16x16x32_bf16 v[114:117], v[170:173], v[178:181], v[114:117]
	v_mfma_f32_16x16x32_bf16 v[106:109], v[162:165], v[192:195], v[106:109]
	v_mfma_f32_16x16x32_bf16 v[98:101], v[170:173], v[192:195], v[98:101]
	v_mfma_f32_16x16x32_bf16 v[90:93], v[162:165], v[200:203], v[90:93]
	v_mfma_f32_16x16x32_bf16 v[82:85], v[170:173], v[200:203], v[82:85]
	v_mfma_f32_16x16x32_bf16 v[74:77], v[162:165], v[208:211], v[74:77]
	v_mfma_f32_16x16x32_bf16 v[66:69], v[170:173], v[208:211], v[66:69]
	v_mfma_f32_16x16x32_bf16 v[122:125], v[166:169], v[182:185], v[122:125]
	v_mfma_f32_16x16x32_bf16 v[114:117], v[174:177], v[182:185], v[114:117]
	v_mfma_f32_16x16x32_bf16 v[106:109], v[166:169], v[196:199], v[106:109]
	v_mfma_f32_16x16x32_bf16 v[98:101], v[174:177], v[196:199], v[98:101]
	v_mfma_f32_16x16x32_bf16 v[90:93], v[166:169], v[204:207], v[90:93]
	v_mfma_f32_16x16x32_bf16 v[82:85], v[174:177], v[204:207], v[82:85]
	v_mfma_f32_16x16x32_bf16 v[74:77], v[166:169], v[212:215], v[74:77]
	v_mfma_f32_16x16x32_bf16 v[66:69], v[174:177], v[212:215], v[66:69]
	s_barrier
	s_setprio 0
	s_add_i32 s1, s51, s31
	v_lshl_add_u64 v[140:141], s[24:25], 0, v[186:187]
	s_mov_b32 m0, s1
	ds_read_b128 v[178:181], v144 offset:16384
	ds_read_b128 v[182:185], v144 offset:17408
	ds_read_b128 v[192:195], v144 offset:18432
	ds_read_b128 v[196:199], v144 offset:19456
	ds_read_b128 v[200:203], v144 offset:20480
	ds_read_b128 v[204:207], v144 offset:21504
	ds_read_b128 v[208:211], v144 offset:22528
	ds_read_b128 v[212:215], v144 offset:23552
	global_load_lds_dwordx4 v[140:141], off
	s_add_i32 m0, s1, 0x2000
	s_add_u32 s52, s24, 0x80000
	v_lshl_add_u64 v[216:217], s[24:25], 0, v[130:131]
	s_addc_u32 s53, s25, 0
	s_add_i32 s0, s0, s31
	global_load_lds_dwordx4 v[216:217], off
	v_lshl_add_u64 v[218:219], s[52:53], 0, v[186:187]
	s_mov_b32 m0, s0
	v_lshl_add_u64 v[220:221], s[26:27], 0, v[132:133]
	global_load_lds_dwordx4 v[218:219], off
	v_lshl_add_u64 v[218:219], s[52:53], 0, v[130:131]
	s_add_i32 m0, s0, 0x2000
	s_nop 0
	global_load_lds_dwordx4 v[218:219], off
	v_lshl_add_u64 v[218:219], s[26:27], 0, v[134:135]
	s_mov_b32 m0, s35
	s_nop 0
	global_load_lds_dwordx4 v[218:219], off
	s_mov_b32 m0, s36
	s_nop 0
	global_load_lds_dwordx4 v[220:221], off
	s_waitcnt vmcnt(8)
	s_waitcnt lgkmcnt(0)
	s_setprio 2
	s_barrier

	v_mfma_f32_16x16x32_bf16 v[62:65], v[146:149], v[178:181], v[62:65]
	v_mfma_f32_16x16x32_bf16 v[54:57], v[154:157], v[178:181], v[54:57]
	v_mfma_f32_16x16x32_bf16 v[46:49], v[146:149], v[192:195], v[46:49]
	v_mfma_f32_16x16x32_bf16 v[38:41], v[154:157], v[192:195], v[38:41]
	v_mfma_f32_16x16x32_bf16 v[30:33], v[146:149], v[200:203], v[30:33]
	v_mfma_f32_16x16x32_bf16 v[22:25], v[154:157], v[200:203], v[22:25]
	v_mfma_f32_16x16x32_bf16 v[14:17], v[146:149], v[208:211], v[14:17]
	v_mfma_f32_16x16x32_bf16 v[6:9], v[154:157], v[208:211], v[6:9]
	v_mfma_f32_16x16x32_bf16 v[62:65], v[150:153], v[182:185], v[62:65]
	v_mfma_f32_16x16x32_bf16 v[54:57], v[158:161], v[182:185], v[54:57]
	v_mfma_f32_16x16x32_bf16 v[46:49], v[150:153], v[196:199], v[46:49]
	v_mfma_f32_16x16x32_bf16 v[38:41], v[158:161], v[196:199], v[38:41]
	v_mfma_f32_16x16x32_bf16 v[30:33], v[150:153], v[204:207], v[30:33]
	v_mfma_f32_16x16x32_bf16 v[22:25], v[158:161], v[204:207], v[22:25]
	v_mfma_f32_16x16x32_bf16 v[14:17], v[150:153], v[212:215], v[14:17]
	v_mfma_f32_16x16x32_bf16 v[6:9], v[158:161], v[212:215], v[6:9]


	v_mfma_f32_16x16x32_bf16 v[58:61], v[162:165], v[178:181], v[58:61]
	v_mfma_f32_16x16x32_bf16 v[50:53], v[170:173], v[178:181], v[50:53]
	v_mfma_f32_16x16x32_bf16 v[42:45], v[162:165], v[192:195], v[42:45]
	v_mfma_f32_16x16x32_bf16 v[34:37], v[170:173], v[192:195], v[34:37]
	v_mfma_f32_16x16x32_bf16 v[26:29], v[162:165], v[200:203], v[26:29]
	v_mfma_f32_16x16x32_bf16 v[18:21], v[170:173], v[200:203], v[18:21]
	v_mfma_f32_16x16x32_bf16 v[10:13], v[162:165], v[208:211], v[10:13]
	v_mfma_f32_16x16x32_bf16 v[2:5], v[170:173], v[208:211], v[2:5]
	v_mfma_f32_16x16x32_bf16 v[58:61], v[166:169], v[182:185], v[58:61]
	v_mfma_f32_16x16x32_bf16 v[50:53], v[174:177], v[182:185], v[50:53]
	v_mfma_f32_16x16x32_bf16 v[42:45], v[166:169], v[196:199], v[42:45]
	v_mfma_f32_16x16x32_bf16 v[34:37], v[174:177], v[196:199], v[34:37]
	v_mfma_f32_16x16x32_bf16 v[26:29], v[166:169], v[204:207], v[26:29]
	v_mfma_f32_16x16x32_bf16 v[18:21], v[174:177], v[204:207], v[18:21]
	v_mfma_f32_16x16x32_bf16 v[10:13], v[166:169], v[212:215], v[10:13]
	v_mfma_f32_16x16x32_bf16 v[2:5], v[174:177], v[212:215], v[2:5]
	s_barrier
	s_setprio 0
	s_add_i32 s0, 0, 0x18000
	v_add_u32_e32 v145, s0, v143
	s_add_i32 s1, 0, 0x1c000
	ds_read_b128 v[146:149], v145
	ds_read_b128 v[150:153], v145 offset:1024
	ds_read_b128 v[154:157], v145 offset:2048
	ds_read_b128 v[158:161], v145 offset:3072
	v_add_u32_e32 v145, s1, v143
	ds_read_b128 v[162:165], v145
	ds_read_b128 v[166:169], v145 offset:1024
	ds_read_b128 v[170:173], v145 offset:2048
	ds_read_b128 v[174:177], v145 offset:3072
	s_add_u32 s26, s26, 0x80000
	s_addc_u32 s27, s27, 0
	s_mov_b32 m0, s37
	v_lshl_add_u64 v[222:223], s[26:27], 0, v[134:135]
	ds_read_b128 v[178:181], v144 offset:32768
	ds_read_b128 v[182:185], v144 offset:33792
	ds_read_b128 v[192:195], v144 offset:34816
	ds_read_b128 v[196:199], v144 offset:35840
	ds_read_b128 v[200:203], v144 offset:36864
	ds_read_b128 v[204:207], v144 offset:37888
	ds_read_b128 v[208:211], v144 offset:38912
	ds_read_b128 v[212:215], v144 offset:39936
	global_load_lds_dwordx4 v[222:223], off
	v_lshl_add_u64 v[222:223], s[26:27], 0, v[132:133]
	s_mov_b32 m0, s38
	s_nop 0
	global_load_lds_dwordx4 v[222:223], off
	s_waitcnt vmcnt(8)
	s_waitcnt lgkmcnt(0)
	s_setprio 2
	s_barrier

	v_mfma_f32_16x16x32_bf16 v[126:129], v[146:149], v[178:181], v[126:129]
	v_mfma_f32_16x16x32_bf16 v[118:121], v[154:157], v[178:181], v[118:121]
	v_mfma_f32_16x16x32_bf16 v[110:113], v[146:149], v[192:195], v[110:113]
	v_mfma_f32_16x16x32_bf16 v[102:105], v[154:157], v[192:195], v[102:105]
	v_mfma_f32_16x16x32_bf16 v[94:97], v[146:149], v[200:203], v[94:97]
	v_mfma_f32_16x16x32_bf16 v[86:89], v[154:157], v[200:203], v[86:89]
	v_mfma_f32_16x16x32_bf16 v[78:81], v[146:149], v[208:211], v[78:81]
	v_mfma_f32_16x16x32_bf16 v[70:73], v[154:157], v[208:211], v[70:73]
	v_mfma_f32_16x16x32_bf16 v[126:129], v[150:153], v[182:185], v[126:129]
	v_mfma_f32_16x16x32_bf16 v[118:121], v[158:161], v[182:185], v[118:121]
	v_mfma_f32_16x16x32_bf16 v[110:113], v[150:153], v[196:199], v[110:113]
	v_mfma_f32_16x16x32_bf16 v[102:105], v[158:161], v[196:199], v[102:105]
	v_mfma_f32_16x16x32_bf16 v[94:97], v[150:153], v[204:207], v[94:97]
	v_mfma_f32_16x16x32_bf16 v[86:89], v[158:161], v[204:207], v[86:89]
	v_mfma_f32_16x16x32_bf16 v[78:81], v[150:153], v[212:215], v[78:81]
	v_mfma_f32_16x16x32_bf16 v[70:73], v[158:161], v[212:215], v[70:73]


	v_mfma_f32_16x16x32_bf16 v[122:125], v[162:165], v[178:181], v[122:125]
	v_mfma_f32_16x16x32_bf16 v[114:117], v[170:173], v[178:181], v[114:117]
	v_mfma_f32_16x16x32_bf16 v[106:109], v[162:165], v[192:195], v[106:109]
	v_mfma_f32_16x16x32_bf16 v[98:101], v[170:173], v[192:195], v[98:101]
	v_mfma_f32_16x16x32_bf16 v[90:93], v[162:165], v[200:203], v[90:93]
	v_mfma_f32_16x16x32_bf16 v[82:85], v[170:173], v[200:203], v[82:85]
	v_mfma_f32_16x16x32_bf16 v[74:77], v[162:165], v[208:211], v[74:77]
	v_mfma_f32_16x16x32_bf16 v[66:69], v[170:173], v[208:211], v[66:69]
	v_mfma_f32_16x16x32_bf16 v[122:125], v[166:169], v[182:185], v[122:125]
	v_mfma_f32_16x16x32_bf16 v[114:117], v[174:177], v[182:185], v[114:117]
	v_mfma_f32_16x16x32_bf16 v[106:109], v[166:169], v[196:199], v[106:109]
	v_mfma_f32_16x16x32_bf16 v[98:101], v[174:177], v[196:199], v[98:101]
	v_mfma_f32_16x16x32_bf16 v[90:93], v[166:169], v[204:207], v[90:93]
	v_mfma_f32_16x16x32_bf16 v[82:85], v[174:177], v[204:207], v[82:85]
	v_mfma_f32_16x16x32_bf16 v[74:77], v[166:169], v[212:215], v[74:77]
	v_mfma_f32_16x16x32_bf16 v[66:69], v[174:177], v[212:215], v[66:69]
	s_barrier
	s_setprio 0
	s_add_i32 s0, s0, s31
	v_lshl_add_u64 v[140:141], v[140:141], 0, s[84:85]
	s_mov_b32 m0, s0
	ds_read_b128 v[178:181], v144 offset:49152
	ds_read_b128 v[182:185], v144 offset:50176
	ds_read_b128 v[192:195], v144 offset:51200
	ds_read_b128 v[196:199], v144 offset:52224
	ds_read_b128 v[200:203], v144 offset:53248
	ds_read_b128 v[204:207], v144 offset:54272
	ds_read_b128 v[208:211], v144 offset:55296
	ds_read_b128 v[212:215], v144 offset:56320
	global_load_lds_dwordx4 v[140:141], off
	s_add_i32 m0, s0, 0x2000
	s_add_u32 s24, s24, 0x80080
	v_lshl_add_u64 v[140:141], v[216:217], 0, s[84:85]
	s_addc_u32 s25, s25, 0
	s_add_i32 s0, s1, s31
	global_load_lds_dwordx4 v[140:141], off
	v_lshl_add_u64 v[140:141], s[24:25], 0, v[186:187]
	s_mov_b32 m0, s0
	s_nop 0
	global_load_lds_dwordx4 v[140:141], off
	v_lshl_add_u64 v[140:141], s[24:25], 0, v[130:131]
	s_add_i32 m0, s0, 0x2000
	s_nop 0
	global_load_lds_dwordx4 v[140:141], off
	v_lshl_add_u64 v[140:141], v[218:219], 0, s[84:85]
	s_mov_b32 m0, s39
	s_nop 0
	global_load_lds_dwordx4 v[140:141], off
	v_lshl_add_u64 v[140:141], v[220:221], 0, s[84:85]
	s_mov_b32 m0, s40
	s_nop 0
	global_load_lds_dwordx4 v[140:141], off
	s_waitcnt vmcnt(8)
	s_waitcnt lgkmcnt(0)
	s_setprio 2
	s_barrier

	v_mfma_f32_16x16x32_bf16 v[62:65], v[146:149], v[178:181], v[62:65]
	v_mfma_f32_16x16x32_bf16 v[54:57], v[154:157], v[178:181], v[54:57]
	v_mfma_f32_16x16x32_bf16 v[46:49], v[146:149], v[192:195], v[46:49]
	v_mfma_f32_16x16x32_bf16 v[38:41], v[154:157], v[192:195], v[38:41]
	v_mfma_f32_16x16x32_bf16 v[30:33], v[146:149], v[200:203], v[30:33]
	v_mfma_f32_16x16x32_bf16 v[22:25], v[154:157], v[200:203], v[22:25]
	v_mfma_f32_16x16x32_bf16 v[14:17], v[146:149], v[208:211], v[14:17]
	v_mfma_f32_16x16x32_bf16 v[6:9], v[154:157], v[208:211], v[6:9]
	v_mfma_f32_16x16x32_bf16 v[62:65], v[150:153], v[182:185], v[62:65]
	v_mfma_f32_16x16x32_bf16 v[54:57], v[158:161], v[182:185], v[54:57]
	v_mfma_f32_16x16x32_bf16 v[46:49], v[150:153], v[196:199], v[46:49]
	v_mfma_f32_16x16x32_bf16 v[38:41], v[158:161], v[196:199], v[38:41]
	v_mfma_f32_16x16x32_bf16 v[30:33], v[150:153], v[204:207], v[30:33]
	v_mfma_f32_16x16x32_bf16 v[22:25], v[158:161], v[204:207], v[22:25]
	v_mfma_f32_16x16x32_bf16 v[14:17], v[150:153], v[212:215], v[14:17]
	v_mfma_f32_16x16x32_bf16 v[6:9], v[158:161], v[212:215], v[6:9]


	v_mfma_f32_16x16x32_bf16 v[58:61], v[162:165], v[178:181], v[58:61]
	v_mfma_f32_16x16x32_bf16 v[50:53], v[170:173], v[178:181], v[50:53]
	v_mfma_f32_16x16x32_bf16 v[42:45], v[162:165], v[192:195], v[42:45]
	v_mfma_f32_16x16x32_bf16 v[34:37], v[170:173], v[192:195], v[34:37]
	v_mfma_f32_16x16x32_bf16 v[26:29], v[162:165], v[200:203], v[26:29]
	v_mfma_f32_16x16x32_bf16 v[18:21], v[170:173], v[200:203], v[18:21]
	v_mfma_f32_16x16x32_bf16 v[10:13], v[162:165], v[208:211], v[10:13]
	v_mfma_f32_16x16x32_bf16 v[2:5], v[170:173], v[208:211], v[2:5]
	v_mfma_f32_16x16x32_bf16 v[58:61], v[166:169], v[182:185], v[58:61]
	v_mfma_f32_16x16x32_bf16 v[50:53], v[174:177], v[182:185], v[50:53]
	v_mfma_f32_16x16x32_bf16 v[42:45], v[166:169], v[196:199], v[42:45]
	v_mfma_f32_16x16x32_bf16 v[34:37], v[174:177], v[196:199], v[34:37]
	v_mfma_f32_16x16x32_bf16 v[26:29], v[166:169], v[204:207], v[26:29]
	v_mfma_f32_16x16x32_bf16 v[18:21], v[174:177], v[204:207], v[18:21]
	v_mfma_f32_16x16x32_bf16 v[10:13], v[166:169], v[212:215], v[10:13]
	v_mfma_f32_16x16x32_bf16 v[2:5], v[174:177], v[212:215], v[2:5]
	s_barrier
	s_setprio 0
	s_add_i32 s50, s50, 2
	s_add_u32 s22, s22, 0x100
	s_addc_u32 s23, s23, 0
	s_add_u32 s48, s48, 0x100
	s_addc_u32 s49, s49, 0
	s_cmp_gt_u32 s50, 29
	s_cbranch_scc0 .LBB0_159
	s_and_b64 vcc, exec, s[10:11]
	s_cbranch_vccz .LBB0_162
	s_barrier

.LBB0_243:
	s_add_u32 s22, s20, 0x100
	s_addc_u32 s23, s21, 0
	s_add_i32 s0, 0, 0x10000
	s_cmpk_eq_i32 s51, 0x54
	s_cselect_b32 s27, s7, s23
	s_cselect_b32 s26, s6, s22
	s_cselect_b32 s25, s19, s50
	s_cselect_b32 s24, s18, s49
	s_add_i32 s1, 0, 0x14000
	v_add_u32_e32 v126, s0, v237
	v_add_u32_e32 v158, s1, v237
	ds_read_b128 v[90:93], v126
	ds_read_b128 v[102:105], v126 offset:1024
	ds_read_b128 v[114:117], v126 offset:2048
	ds_read_b128 v[126:129], v126 offset:3072
	ds_read_b128 v[138:141], v158
	ds_read_b128 v[142:145], v158 offset:1024
	ds_read_b128 v[154:157], v158 offset:2048
	ds_read_b128 v[158:161], v158 offset:3072
	v_lshl_add_u64 v[210:211], s[20:21], 0, v[198:199]
	s_add_i32 m0, s34, 0xc000
	ds_read_b128 v[162:165], v238
	ds_read_b128 v[166:169], v238 offset:1024
	ds_read_b128 v[170:173], v238 offset:2048
	ds_read_b128 v[174:177], v238 offset:3072
	ds_read_b128 v[178:181], v238 offset:4096
	ds_read_b128 v[182:185], v238 offset:5120
	ds_read_b128 v[202:205], v238 offset:6144
	ds_read_b128 v[206:209], v238 offset:7168
	global_load_lds_dwordx4 v[210:211], off
	v_lshl_add_u64 v[210:211], s[20:21], 0, v[200:201]
	s_add_i32 m0, s34, 0xe000
	s_nop 0
	global_load_lds_dwordx4 v[210:211], off
	s_waitcnt vmcnt(8)
	s_waitcnt lgkmcnt(0)
	s_setprio 2
	s_barrier

	v_mfma_f32_16x16x32_bf16 v[150:153], v[90:93], v[162:165], v[150:153]
	v_mfma_f32_16x16x32_bf16 v[146:149], v[114:117], v[162:165], v[146:149]
	v_mfma_f32_16x16x32_bf16 v[122:125], v[90:93], v[170:173], v[122:125]
	v_mfma_f32_16x16x32_bf16 v[118:121], v[114:117], v[170:173], v[118:121]
	v_mfma_f32_16x16x32_bf16 v[98:101], v[90:93], v[178:181], v[98:101]
	v_mfma_f32_16x16x32_bf16 v[94:97], v[114:117], v[178:181], v[94:97]
	v_mfma_f32_16x16x32_bf16 v[78:81], v[90:93], v[202:205], v[78:81]
	v_mfma_f32_16x16x32_bf16 v[74:77], v[114:117], v[202:205], v[74:77]
	v_mfma_f32_16x16x32_bf16 v[150:153], v[102:105], v[166:169], v[150:153]
	v_mfma_f32_16x16x32_bf16 v[146:149], v[126:129], v[166:169], v[146:149]
	v_mfma_f32_16x16x32_bf16 v[122:125], v[102:105], v[174:177], v[122:125]
	v_mfma_f32_16x16x32_bf16 v[118:121], v[126:129], v[174:177], v[118:121]
	v_mfma_f32_16x16x32_bf16 v[98:101], v[102:105], v[182:185], v[98:101]
	v_mfma_f32_16x16x32_bf16 v[94:97], v[126:129], v[182:185], v[94:97]
	v_mfma_f32_16x16x32_bf16 v[78:81], v[102:105], v[206:209], v[78:81]
	v_mfma_f32_16x16x32_bf16 v[74:77], v[126:129], v[206:209], v[74:77]


	v_mfma_f32_16x16x32_bf16 v[134:137], v[138:141], v[162:165], v[134:137]
	v_mfma_f32_16x16x32_bf16 v[130:133], v[154:157], v[162:165], v[130:133]
	v_mfma_f32_16x16x32_bf16 v[110:113], v[138:141], v[170:173], v[110:113]
	v_mfma_f32_16x16x32_bf16 v[106:109], v[154:157], v[170:173], v[106:109]
	v_mfma_f32_16x16x32_bf16 v[86:89], v[138:141], v[178:181], v[86:89]
	v_mfma_f32_16x16x32_bf16 v[82:85], v[154:157], v[178:181], v[82:85]
	v_mfma_f32_16x16x32_bf16 v[70:73], v[138:141], v[202:205], v[70:73]
	v_mfma_f32_16x16x32_bf16 v[66:69], v[154:157], v[202:205], v[66:69]
	v_mfma_f32_16x16x32_bf16 v[134:137], v[142:145], v[166:169], v[134:137]
	v_mfma_f32_16x16x32_bf16 v[130:133], v[158:161], v[166:169], v[130:133]
	v_mfma_f32_16x16x32_bf16 v[110:113], v[142:145], v[174:177], v[110:113]
	v_mfma_f32_16x16x32_bf16 v[106:109], v[158:161], v[174:177], v[106:109]
	v_mfma_f32_16x16x32_bf16 v[86:89], v[142:145], v[182:185], v[86:89]
	v_mfma_f32_16x16x32_bf16 v[82:85], v[158:161], v[182:185], v[82:85]
	v_mfma_f32_16x16x32_bf16 v[70:73], v[142:145], v[206:209], v[70:73]
	v_mfma_f32_16x16x32_bf16 v[66:69], v[158:161], v[206:209], v[66:69]
	s_barrier
	s_setprio 0
	s_add_i32 s0, s0, s31
	v_lshl_add_u64 v[210:211], s[24:25], 0, v[186:187]
	s_mov_b32 m0, s0
	ds_read_b128 v[162:165], v238 offset:16384
	ds_read_b128 v[166:169], v238 offset:17408
	ds_read_b128 v[170:173], v238 offset:18432
	ds_read_b128 v[174:177], v238 offset:19456
	ds_read_b128 v[178:181], v238 offset:20480
	ds_read_b128 v[182:185], v238 offset:21504
	ds_read_b128 v[202:205], v238 offset:22528
	ds_read_b128 v[206:209], v238 offset:23552
	global_load_lds_dwordx4 v[210:211], off
	s_add_i32 m0, s0, 0x2000
	s_add_u32 s20, s24, 0x160000
	v_lshl_add_u64 v[212:213], s[24:25], 0, v[196:197]
	s_addc_u32 s21, s25, 0
	s_add_i32 s0, s1, s31
	global_load_lds_dwordx4 v[212:213], off
	v_lshl_add_u64 v[214:215], s[20:21], 0, v[186:187]
	s_mov_b32 m0, s0
	v_lshl_add_u64 v[216:217], s[26:27], 0, v[194:195]
	global_load_lds_dwordx4 v[214:215], off
	v_lshl_add_u64 v[214:215], s[20:21], 0, v[196:197]
	s_add_i32 m0, s0, 0x2000
	s_nop 0
	global_load_lds_dwordx4 v[214:215], off
	v_lshl_add_u64 v[214:215], s[26:27], 0, v[192:193]
	s_mov_b32 m0, s34
	s_nop 0
	global_load_lds_dwordx4 v[214:215], off
	s_mov_b32 m0, s35
	s_nop 0
	global_load_lds_dwordx4 v[216:217], off
	s_waitcnt vmcnt(8)
	s_waitcnt lgkmcnt(0)
	s_setprio 2
	s_barrier

	v_mfma_f32_16x16x32_bf16 v[62:65], v[90:93], v[162:165], v[62:65]
	v_mfma_f32_16x16x32_bf16 v[58:61], v[114:117], v[162:165], v[58:61]
	v_mfma_f32_16x16x32_bf16 v[46:49], v[90:93], v[170:173], v[46:49]
	v_mfma_f32_16x16x32_bf16 v[42:45], v[114:117], v[170:173], v[42:45]
	v_mfma_f32_16x16x32_bf16 v[30:33], v[90:93], v[178:181], v[30:33]
	v_mfma_f32_16x16x32_bf16 v[26:29], v[114:117], v[178:181], v[26:29]
	v_mfma_f32_16x16x32_bf16 v[14:17], v[90:93], v[202:205], v[14:17]
	v_mfma_f32_16x16x32_bf16 v[10:13], v[114:117], v[202:205], v[10:13]
	v_mfma_f32_16x16x32_bf16 v[62:65], v[102:105], v[166:169], v[62:65]
	v_mfma_f32_16x16x32_bf16 v[58:61], v[126:129], v[166:169], v[58:61]
	v_mfma_f32_16x16x32_bf16 v[46:49], v[102:105], v[174:177], v[46:49]
	v_mfma_f32_16x16x32_bf16 v[42:45], v[126:129], v[174:177], v[42:45]
	v_mfma_f32_16x16x32_bf16 v[30:33], v[102:105], v[182:185], v[30:33]
	v_mfma_f32_16x16x32_bf16 v[26:29], v[126:129], v[182:185], v[26:29]
	v_mfma_f32_16x16x32_bf16 v[14:17], v[102:105], v[206:209], v[14:17]
	v_mfma_f32_16x16x32_bf16 v[10:13], v[126:129], v[206:209], v[10:13]


	v_mfma_f32_16x16x32_bf16 v[54:57], v[138:141], v[162:165], v[54:57]
	v_mfma_f32_16x16x32_bf16 v[50:53], v[154:157], v[162:165], v[50:53]
	v_mfma_f32_16x16x32_bf16 v[38:41], v[138:141], v[170:173], v[38:41]
	v_mfma_f32_16x16x32_bf16 v[34:37], v[154:157], v[170:173], v[34:37]
	v_mfma_f32_16x16x32_bf16 v[22:25], v[138:141], v[178:181], v[22:25]
	v_mfma_f32_16x16x32_bf16 v[18:21], v[154:157], v[178:181], v[18:21]
	v_mfma_f32_16x16x32_bf16 v[6:9], v[138:141], v[202:205], v[6:9]
	v_mfma_f32_16x16x32_bf16 v[2:5], v[154:157], v[202:205], v[2:5]
	v_mfma_f32_16x16x32_bf16 v[54:57], v[142:145], v[166:169], v[54:57]
	v_mfma_f32_16x16x32_bf16 v[50:53], v[158:161], v[166:169], v[50:53]
	v_mfma_f32_16x16x32_bf16 v[38:41], v[142:145], v[174:177], v[38:41]
	v_mfma_f32_16x16x32_bf16 v[34:37], v[158:161], v[174:177], v[34:37]
	v_mfma_f32_16x16x32_bf16 v[22:25], v[142:145], v[182:185], v[22:25]
	v_mfma_f32_16x16x32_bf16 v[18:21], v[158:161], v[182:185], v[18:21]
	v_mfma_f32_16x16x32_bf16 v[6:9], v[142:145], v[206:209], v[6:9]
	v_mfma_f32_16x16x32_bf16 v[2:5], v[158:161], v[206:209], v[2:5]
	s_barrier
	s_setprio 0
	s_add_i32 s0, 0, 0x18000
	s_add_i32 s1, 0, 0x1c000
	v_add_u32_e32 v126, s0, v237
	v_add_u32_e32 v158, s1, v237
	ds_read_b128 v[90:93], v126
	ds_read_b128 v[102:105], v126 offset:1024
	ds_read_b128 v[114:117], v126 offset:2048
	ds_read_b128 v[126:129], v126 offset:3072
	ds_read_b128 v[138:141], v158
	ds_read_b128 v[142:145], v158 offset:1024
	ds_read_b128 v[154:157], v158 offset:2048
	ds_read_b128 v[158:161], v158 offset:3072
	s_add_u32 s20, s26, 0x160000
	s_addc_u32 s21, s27, 0
	s_mov_b32 m0, s36
	v_lshl_add_u64 v[218:219], s[20:21], 0, v[192:193]
	ds_read_b128 v[162:165], v238 offset:32768
	ds_read_b128 v[166:169], v238 offset:33792
	ds_read_b128 v[170:173], v238 offset:34816
	ds_read_b128 v[174:177], v238 offset:35840
	ds_read_b128 v[178:181], v238 offset:36864
	ds_read_b128 v[182:185], v238 offset:37888
	ds_read_b128 v[202:205], v238 offset:38912
	ds_read_b128 v[206:209], v238 offset:39936
	global_load_lds_dwordx4 v[218:219], off
	v_lshl_add_u64 v[218:219], s[20:21], 0, v[194:195]
	s_mov_b32 m0, s37
	s_nop 0
	global_load_lds_dwordx4 v[218:219], off
	s_waitcnt vmcnt(8)
	s_waitcnt lgkmcnt(0)
	s_setprio 2
	s_barrier

	v_mfma_f32_16x16x32_bf16 v[150:153], v[90:93], v[162:165], v[150:153]
	v_mfma_f32_16x16x32_bf16 v[146:149], v[114:117], v[162:165], v[146:149]
	v_mfma_f32_16x16x32_bf16 v[122:125], v[90:93], v[170:173], v[122:125]
	v_mfma_f32_16x16x32_bf16 v[118:121], v[114:117], v[170:173], v[118:121]
	v_mfma_f32_16x16x32_bf16 v[98:101], v[90:93], v[178:181], v[98:101]
	v_mfma_f32_16x16x32_bf16 v[94:97], v[114:117], v[178:181], v[94:97]
	v_mfma_f32_16x16x32_bf16 v[78:81], v[90:93], v[202:205], v[78:81]
	v_mfma_f32_16x16x32_bf16 v[74:77], v[114:117], v[202:205], v[74:77]
	v_mfma_f32_16x16x32_bf16 v[150:153], v[102:105], v[166:169], v[150:153]
	v_mfma_f32_16x16x32_bf16 v[146:149], v[126:129], v[166:169], v[146:149]
	v_mfma_f32_16x16x32_bf16 v[122:125], v[102:105], v[174:177], v[122:125]
	v_mfma_f32_16x16x32_bf16 v[118:121], v[126:129], v[174:177], v[118:121]
	v_mfma_f32_16x16x32_bf16 v[98:101], v[102:105], v[182:185], v[98:101]
	v_mfma_f32_16x16x32_bf16 v[94:97], v[126:129], v[182:185], v[94:97]
	v_mfma_f32_16x16x32_bf16 v[78:81], v[102:105], v[206:209], v[78:81]
	v_mfma_f32_16x16x32_bf16 v[74:77], v[126:129], v[206:209], v[74:77]


	v_mfma_f32_16x16x32_bf16 v[134:137], v[138:141], v[162:165], v[134:137]
	v_mfma_f32_16x16x32_bf16 v[130:133], v[154:157], v[162:165], v[130:133]
	v_mfma_f32_16x16x32_bf16 v[110:113], v[138:141], v[170:173], v[110:113]
	v_mfma_f32_16x16x32_bf16 v[106:109], v[154:157], v[170:173], v[106:109]
	v_mfma_f32_16x16x32_bf16 v[86:89], v[138:141], v[178:181], v[86:89]
	v_mfma_f32_16x16x32_bf16 v[82:85], v[154:157], v[178:181], v[82:85]
	v_mfma_f32_16x16x32_bf16 v[70:73], v[138:141], v[202:205], v[70:73]
	v_mfma_f32_16x16x32_bf16 v[66:69], v[154:157], v[202:205], v[66:69]
	v_mfma_f32_16x16x32_bf16 v[134:137], v[142:145], v[166:169], v[134:137]
	v_mfma_f32_16x16x32_bf16 v[130:133], v[158:161], v[166:169], v[130:133]
	v_mfma_f32_16x16x32_bf16 v[110:113], v[142:145], v[174:177], v[110:113]
	v_mfma_f32_16x16x32_bf16 v[106:109], v[158:161], v[174:177], v[106:109]
	v_mfma_f32_16x16x32_bf16 v[86:89], v[142:145], v[182:185], v[86:89]
	v_mfma_f32_16x16x32_bf16 v[82:85], v[158:161], v[182:185], v[82:85]
	v_mfma_f32_16x16x32_bf16 v[70:73], v[142:145], v[206:209], v[70:73]
	v_mfma_f32_16x16x32_bf16 v[66:69], v[158:161], v[206:209], v[66:69]
	s_barrier
	s_setprio 0
	s_add_i32 s0, s0, s31
	v_lshl_add_u64 v[210:211], v[210:211], 0, s[84:85]
	s_mov_b32 m0, s0
	ds_read_b128 v[162:165], v238 offset:49152
	ds_read_b128 v[166:169], v238 offset:50176
	ds_read_b128 v[170:173], v238 offset:51200
	ds_read_b128 v[174:177], v238 offset:52224
	ds_read_b128 v[178:181], v238 offset:53248
	ds_read_b128 v[182:185], v238 offset:54272
	ds_read_b128 v[202:205], v238 offset:55296
	ds_read_b128 v[206:209], v238 offset:56320
	global_load_lds_dwordx4 v[210:211], off
	s_add_i32 m0, s0, 0x2000
	s_add_u32 s20, s24, 0x160080
	v_lshl_add_u64 v[210:211], v[212:213], 0, s[84:85]
	s_addc_u32 s21, s25, 0
	s_add_i32 s0, s1, s31
	global_load_lds_dwordx4 v[210:211], off
	v_lshl_add_u64 v[210:211], s[20:21], 0, v[186:187]
	s_mov_b32 m0, s0
	s_nop 0
	global_load_lds_dwordx4 v[210:211], off
	v_lshl_add_u64 v[210:211], s[20:21], 0, v[196:197]
	s_add_i32 m0, s0, 0x2000
	s_nop 0
	global_load_lds_dwordx4 v[210:211], off
	v_lshl_add_u64 v[210:211], v[214:215], 0, s[84:85]
	s_mov_b32 m0, s41
	s_nop 0
	global_load_lds_dwordx4 v[210:211], off
	v_lshl_add_u64 v[210:211], v[216:217], 0, s[84:85]
	s_mov_b32 m0, s42
	s_nop 0
	global_load_lds_dwordx4 v[210:211], off
	s_waitcnt vmcnt(8)
	s_waitcnt lgkmcnt(0)
	s_setprio 2
	s_barrier

	v_mfma_f32_16x16x32_bf16 v[62:65], v[90:93], v[162:165], v[62:65]
	v_mfma_f32_16x16x32_bf16 v[58:61], v[114:117], v[162:165], v[58:61]
	v_mfma_f32_16x16x32_bf16 v[46:49], v[90:93], v[170:173], v[46:49]
	v_mfma_f32_16x16x32_bf16 v[42:45], v[114:117], v[170:173], v[42:45]
	v_mfma_f32_16x16x32_bf16 v[30:33], v[90:93], v[178:181], v[30:33]
	v_mfma_f32_16x16x32_bf16 v[26:29], v[114:117], v[178:181], v[26:29]
	v_mfma_f32_16x16x32_bf16 v[14:17], v[90:93], v[202:205], v[14:17]
	v_mfma_f32_16x16x32_bf16 v[10:13], v[114:117], v[202:205], v[10:13]
	v_mfma_f32_16x16x32_bf16 v[62:65], v[102:105], v[166:169], v[62:65]
	v_mfma_f32_16x16x32_bf16 v[58:61], v[126:129], v[166:169], v[58:61]
	v_mfma_f32_16x16x32_bf16 v[46:49], v[102:105], v[174:177], v[46:49]
	v_mfma_f32_16x16x32_bf16 v[42:45], v[126:129], v[174:177], v[42:45]
	v_mfma_f32_16x16x32_bf16 v[30:33], v[102:105], v[182:185], v[30:33]
	v_mfma_f32_16x16x32_bf16 v[26:29], v[126:129], v[182:185], v[26:29]
	v_mfma_f32_16x16x32_bf16 v[14:17], v[102:105], v[206:209], v[14:17]
	v_mfma_f32_16x16x32_bf16 v[10:13], v[126:129], v[206:209], v[10:13]


	v_mfma_f32_16x16x32_bf16 v[54:57], v[138:141], v[162:165], v[54:57]
	v_mfma_f32_16x16x32_bf16 v[50:53], v[154:157], v[162:165], v[50:53]
	v_mfma_f32_16x16x32_bf16 v[38:41], v[138:141], v[170:173], v[38:41]
	v_mfma_f32_16x16x32_bf16 v[34:37], v[154:157], v[170:173], v[34:37]
	v_mfma_f32_16x16x32_bf16 v[22:25], v[138:141], v[178:181], v[22:25]
	v_mfma_f32_16x16x32_bf16 v[18:21], v[154:157], v[178:181], v[18:21]
	v_mfma_f32_16x16x32_bf16 v[6:9], v[138:141], v[202:205], v[6:9]
	v_mfma_f32_16x16x32_bf16 v[2:5], v[154:157], v[202:205], v[2:5]
	v_mfma_f32_16x16x32_bf16 v[54:57], v[142:145], v[166:169], v[54:57]
	v_mfma_f32_16x16x32_bf16 v[50:53], v[158:161], v[166:169], v[50:53]
	v_mfma_f32_16x16x32_bf16 v[38:41], v[142:145], v[174:177], v[38:41]
	v_mfma_f32_16x16x32_bf16 v[34:37], v[158:161], v[174:177], v[34:37]
	v_mfma_f32_16x16x32_bf16 v[22:25], v[142:145], v[182:185], v[22:25]
	v_mfma_f32_16x16x32_bf16 v[18:21], v[158:161], v[182:185], v[18:21]
	v_mfma_f32_16x16x32_bf16 v[6:9], v[142:145], v[206:209], v[6:9]
	v_mfma_f32_16x16x32_bf16 v[2:5], v[158:161], v[206:209], v[2:5]
	s_barrier
	s_setprio 0
	s_add_i32 s51, s51, 2
	s_add_u32 s49, s49, 0x100
	s_addc_u32 s50, s50, 0
	s_cmpk_gt_u32 s51, 0x55
	s_mov_b64 s[20:21], s[22:23]
	s_cbranch_scc0 .LBB0_243
	s_and_b64 vcc, exec, s[16:17]
	s_cbranch_vccz .LBB0_246
	s_barrier

.LBB0_443:
	s_add_u32 s0, s26, 0xfff80080
	s_addc_u32 s1, s27, -1
	s_add_i32 s56, 0, 0x10000
	s_cmp_eq_u32 s55, 28
	s_cselect_b32 s31, s19, s1
	s_cselect_b32 s30, s51, s0
	v_add_u32_e32 v140, s56, v144
	s_cselect_b32 s29, s17, s54
	s_cselect_b32 s28, s52, s53
	s_add_i32 s0, 0, 0x14000
	ds_read_b128 v[146:149], v140
	ds_read_b128 v[150:153], v140 offset:1024
	ds_read_b128 v[154:157], v140 offset:2048
	ds_read_b128 v[158:161], v140 offset:3072
	v_add_u32_e32 v140, s0, v144
	ds_read_b128 v[162:165], v140
	ds_read_b128 v[166:169], v140 offset:1024
	ds_read_b128 v[170:173], v140 offset:2048
	ds_read_b128 v[174:177], v140 offset:3072
	v_lshl_add_u64 v[140:141], s[26:27], 0, v[136:137]
	s_add_i32 m0, s25, 0xc000
	ds_read_b128 v[178:181], v145
	ds_read_b128 v[182:185], v145 offset:1024
	ds_read_b128 v[192:195], v145 offset:2048
	ds_read_b128 v[196:199], v145 offset:3072
	ds_read_b128 v[200:203], v145 offset:4096
	ds_read_b128 v[204:207], v145 offset:5120
	ds_read_b128 v[208:211], v145 offset:6144
	ds_read_b128 v[212:215], v145 offset:7168
	global_load_lds_dwordx4 v[140:141], off
	v_lshl_add_u64 v[140:141], s[26:27], 0, v[138:139]
	s_add_i32 m0, s25, 0xe000
	s_nop 0
	global_load_lds_dwordx4 v[140:141], off
	s_waitcnt vmcnt(8)
	s_waitcnt lgkmcnt(0)
	s_setprio 2
	s_barrier

	v_mfma_f32_16x16x32_bf16 v[126:129], v[146:149], v[178:181], v[126:129]
	v_mfma_f32_16x16x32_bf16 v[122:125], v[154:157], v[178:181], v[122:125]
	v_mfma_f32_16x16x32_bf16 v[114:117], v[146:149], v[192:195], v[114:117]
	v_mfma_f32_16x16x32_bf16 v[106:109], v[154:157], v[192:195], v[106:109]
	v_mfma_f32_16x16x32_bf16 v[98:101], v[146:149], v[200:203], v[98:101]
	v_mfma_f32_16x16x32_bf16 v[90:93], v[154:157], v[200:203], v[90:93]
	v_mfma_f32_16x16x32_bf16 v[82:85], v[146:149], v[208:211], v[82:85]
	v_mfma_f32_16x16x32_bf16 v[74:77], v[154:157], v[208:211], v[74:77]
	v_mfma_f32_16x16x32_bf16 v[126:129], v[150:153], v[182:185], v[126:129]
	v_mfma_f32_16x16x32_bf16 v[122:125], v[158:161], v[182:185], v[122:125]
	v_mfma_f32_16x16x32_bf16 v[114:117], v[150:153], v[196:199], v[114:117]
	v_mfma_f32_16x16x32_bf16 v[106:109], v[158:161], v[196:199], v[106:109]
	v_mfma_f32_16x16x32_bf16 v[98:101], v[150:153], v[204:207], v[98:101]
	v_mfma_f32_16x16x32_bf16 v[90:93], v[158:161], v[204:207], v[90:93]
	v_mfma_f32_16x16x32_bf16 v[82:85], v[150:153], v[212:215], v[82:85]
	v_mfma_f32_16x16x32_bf16 v[74:77], v[158:161], v[212:215], v[74:77]


	v_mfma_f32_16x16x32_bf16 v[118:121], v[162:165], v[178:181], v[118:121]
	v_mfma_f32_16x16x32_bf16 v[110:113], v[170:173], v[178:181], v[110:113]
	v_mfma_f32_16x16x32_bf16 v[102:105], v[162:165], v[192:195], v[102:105]
	v_mfma_f32_16x16x32_bf16 v[94:97], v[170:173], v[192:195], v[94:97]
	v_mfma_f32_16x16x32_bf16 v[86:89], v[162:165], v[200:203], v[86:89]
	v_mfma_f32_16x16x32_bf16 v[78:81], v[170:173], v[200:203], v[78:81]
	v_mfma_f32_16x16x32_bf16 v[70:73], v[162:165], v[208:211], v[70:73]
	v_mfma_f32_16x16x32_bf16 v[66:69], v[170:173], v[208:211], v[66:69]
	v_mfma_f32_16x16x32_bf16 v[118:121], v[166:169], v[182:185], v[118:121]
	v_mfma_f32_16x16x32_bf16 v[110:113], v[174:177], v[182:185], v[110:113]
	v_mfma_f32_16x16x32_bf16 v[102:105], v[166:169], v[196:199], v[102:105]
	v_mfma_f32_16x16x32_bf16 v[94:97], v[174:177], v[196:199], v[94:97]
	v_mfma_f32_16x16x32_bf16 v[86:89], v[166:169], v[204:207], v[86:89]
	v_mfma_f32_16x16x32_bf16 v[78:81], v[174:177], v[204:207], v[78:81]
	v_mfma_f32_16x16x32_bf16 v[70:73], v[166:169], v[212:215], v[70:73]
	v_mfma_f32_16x16x32_bf16 v[66:69], v[174:177], v[212:215], v[66:69]
	s_barrier
	s_setprio 0
	s_add_i32 s1, s56, s39
	v_lshl_add_u64 v[140:141], s[28:29], 0, v[186:187]
	s_mov_b32 m0, s1
	ds_read_b128 v[178:181], v145 offset:16384
	ds_read_b128 v[182:185], v145 offset:17408
	ds_read_b128 v[192:195], v145 offset:18432
	ds_read_b128 v[196:199], v145 offset:19456
	ds_read_b128 v[200:203], v145 offset:20480
	ds_read_b128 v[204:207], v145 offset:21504
	ds_read_b128 v[208:211], v145 offset:22528
	ds_read_b128 v[212:215], v145 offset:23552
	global_load_lds_dwordx4 v[140:141], off
	s_add_i32 m0, s1, 0x2000
	s_add_u32 s56, s28, 0x80000
	v_lshl_add_u64 v[188:189], s[28:29], 0, v[130:131]
	s_addc_u32 s57, s29, 0
	s_add_i32 s0, s0, s39
	global_load_lds_dwordx4 v[188:189], off
	v_lshl_add_u64 v[216:217], s[56:57], 0, v[186:187]
	s_mov_b32 m0, s0
	v_lshl_add_u64 v[218:219], s[30:31], 0, v[132:133]
	global_load_lds_dwordx4 v[216:217], off
	v_lshl_add_u64 v[216:217], s[56:57], 0, v[130:131]
	s_add_i32 m0, s0, 0x2000
	s_nop 0
	global_load_lds_dwordx4 v[216:217], off
	v_lshl_add_u64 v[216:217], s[30:31], 0, v[134:135]
	s_mov_b32 m0, s25
	s_nop 0
	global_load_lds_dwordx4 v[216:217], off
	s_mov_b32 m0, s40
	s_nop 0
	global_load_lds_dwordx4 v[218:219], off
	s_waitcnt vmcnt(8)
	s_waitcnt lgkmcnt(0)
	s_setprio 2
	s_barrier

	v_mfma_f32_16x16x32_bf16 v[62:65], v[146:149], v[178:181], v[62:65]
	v_mfma_f32_16x16x32_bf16 v[58:61], v[154:157], v[178:181], v[58:61]
	v_mfma_f32_16x16x32_bf16 v[50:53], v[146:149], v[192:195], v[50:53]
	v_mfma_f32_16x16x32_bf16 v[42:45], v[154:157], v[192:195], v[42:45]
	v_mfma_f32_16x16x32_bf16 v[34:37], v[146:149], v[200:203], v[34:37]
	v_mfma_f32_16x16x32_bf16 v[26:29], v[154:157], v[200:203], v[26:29]
	v_mfma_f32_16x16x32_bf16 v[18:21], v[146:149], v[208:211], v[18:21]
	v_mfma_f32_16x16x32_bf16 v[10:13], v[154:157], v[208:211], v[10:13]
	v_mfma_f32_16x16x32_bf16 v[62:65], v[150:153], v[182:185], v[62:65]
	v_mfma_f32_16x16x32_bf16 v[58:61], v[158:161], v[182:185], v[58:61]
	v_mfma_f32_16x16x32_bf16 v[50:53], v[150:153], v[196:199], v[50:53]
	v_mfma_f32_16x16x32_bf16 v[42:45], v[158:161], v[196:199], v[42:45]
	v_mfma_f32_16x16x32_bf16 v[34:37], v[150:153], v[204:207], v[34:37]
	v_mfma_f32_16x16x32_bf16 v[26:29], v[158:161], v[204:207], v[26:29]
	v_mfma_f32_16x16x32_bf16 v[18:21], v[150:153], v[212:215], v[18:21]
	v_mfma_f32_16x16x32_bf16 v[10:13], v[158:161], v[212:215], v[10:13]


	v_mfma_f32_16x16x32_bf16 v[54:57], v[162:165], v[178:181], v[54:57]
	v_mfma_f32_16x16x32_bf16 v[46:49], v[170:173], v[178:181], v[46:49]
	v_mfma_f32_16x16x32_bf16 v[38:41], v[162:165], v[192:195], v[38:41]
	v_mfma_f32_16x16x32_bf16 v[30:33], v[170:173], v[192:195], v[30:33]
	v_mfma_f32_16x16x32_bf16 v[22:25], v[162:165], v[200:203], v[22:25]
	v_mfma_f32_16x16x32_bf16 v[14:17], v[170:173], v[200:203], v[14:17]
	v_mfma_f32_16x16x32_bf16 v[6:9], v[162:165], v[208:211], v[6:9]
	v_mfma_f32_16x16x32_bf16 v[2:5], v[170:173], v[208:211], v[2:5]
	v_mfma_f32_16x16x32_bf16 v[54:57], v[166:169], v[182:185], v[54:57]
	v_mfma_f32_16x16x32_bf16 v[46:49], v[174:177], v[182:185], v[46:49]
	v_mfma_f32_16x16x32_bf16 v[38:41], v[166:169], v[196:199], v[38:41]
	v_mfma_f32_16x16x32_bf16 v[30:33], v[174:177], v[196:199], v[30:33]
	v_mfma_f32_16x16x32_bf16 v[22:25], v[166:169], v[204:207], v[22:25]
	v_mfma_f32_16x16x32_bf16 v[14:17], v[174:177], v[204:207], v[14:17]
	v_mfma_f32_16x16x32_bf16 v[6:9], v[166:169], v[212:215], v[6:9]
	v_mfma_f32_16x16x32_bf16 v[2:5], v[174:177], v[212:215], v[2:5]
	s_barrier
	s_setprio 0
	s_add_i32 s0, 0, 0x18000
	s_add_i32 s1, 0, 0x1c000
	v_add_u32_e32 v158, s0, v144
	v_add_u32_e32 v174, s1, v144
	ds_read_b128 v[146:149], v158
	ds_read_b128 v[150:153], v158 offset:1024
	ds_read_b128 v[154:157], v158 offset:2048
	ds_read_b128 v[158:161], v158 offset:3072
	ds_read_b128 v[162:165], v174
	ds_read_b128 v[166:169], v174 offset:1024
	ds_read_b128 v[170:173], v174 offset:2048
	ds_read_b128 v[174:177], v174 offset:3072
	s_add_u32 s30, s30, 0x80000
	s_addc_u32 s31, s31, 0
	s_mov_b32 m0, s41
	v_lshl_add_u64 v[220:221], s[30:31], 0, v[134:135]
	ds_read_b128 v[178:181], v145 offset:32768
	ds_read_b128 v[182:185], v145 offset:33792
	ds_read_b128 v[192:195], v145 offset:34816
	ds_read_b128 v[196:199], v145 offset:35840
	ds_read_b128 v[200:203], v145 offset:36864
	ds_read_b128 v[204:207], v145 offset:37888
	ds_read_b128 v[208:211], v145 offset:38912
	ds_read_b128 v[212:215], v145 offset:39936
	global_load_lds_dwordx4 v[220:221], off
	v_lshl_add_u64 v[220:221], s[30:31], 0, v[132:133]
	s_mov_b32 m0, s42
	s_nop 0
	global_load_lds_dwordx4 v[220:221], off
	s_waitcnt vmcnt(8)
	s_waitcnt lgkmcnt(0)
	s_setprio 2
	s_barrier

	v_mfma_f32_16x16x32_bf16 v[126:129], v[146:149], v[178:181], v[126:129]
	v_mfma_f32_16x16x32_bf16 v[122:125], v[154:157], v[178:181], v[122:125]
	v_mfma_f32_16x16x32_bf16 v[114:117], v[146:149], v[192:195], v[114:117]
	v_mfma_f32_16x16x32_bf16 v[106:109], v[154:157], v[192:195], v[106:109]
	v_mfma_f32_16x16x32_bf16 v[98:101], v[146:149], v[200:203], v[98:101]
	v_mfma_f32_16x16x32_bf16 v[90:93], v[154:157], v[200:203], v[90:93]
	v_mfma_f32_16x16x32_bf16 v[82:85], v[146:149], v[208:211], v[82:85]
	v_mfma_f32_16x16x32_bf16 v[74:77], v[154:157], v[208:211], v[74:77]
	v_mfma_f32_16x16x32_bf16 v[126:129], v[150:153], v[182:185], v[126:129]
	v_mfma_f32_16x16x32_bf16 v[122:125], v[158:161], v[182:185], v[122:125]
	v_mfma_f32_16x16x32_bf16 v[114:117], v[150:153], v[196:199], v[114:117]
	v_mfma_f32_16x16x32_bf16 v[106:109], v[158:161], v[196:199], v[106:109]
	v_mfma_f32_16x16x32_bf16 v[98:101], v[150:153], v[204:207], v[98:101]
	v_mfma_f32_16x16x32_bf16 v[90:93], v[158:161], v[204:207], v[90:93]
	v_mfma_f32_16x16x32_bf16 v[82:85], v[150:153], v[212:215], v[82:85]
	v_mfma_f32_16x16x32_bf16 v[74:77], v[158:161], v[212:215], v[74:77]


	v_mfma_f32_16x16x32_bf16 v[118:121], v[162:165], v[178:181], v[118:121]
	v_mfma_f32_16x16x32_bf16 v[110:113], v[170:173], v[178:181], v[110:113]
	v_mfma_f32_16x16x32_bf16 v[102:105], v[162:165], v[192:195], v[102:105]
	v_mfma_f32_16x16x32_bf16 v[94:97], v[170:173], v[192:195], v[94:97]
	v_mfma_f32_16x16x32_bf16 v[86:89], v[162:165], v[200:203], v[86:89]
	v_mfma_f32_16x16x32_bf16 v[78:81], v[170:173], v[200:203], v[78:81]
	v_mfma_f32_16x16x32_bf16 v[70:73], v[162:165], v[208:211], v[70:73]
	v_mfma_f32_16x16x32_bf16 v[66:69], v[170:173], v[208:211], v[66:69]
	v_mfma_f32_16x16x32_bf16 v[118:121], v[166:169], v[182:185], v[118:121]
	v_mfma_f32_16x16x32_bf16 v[110:113], v[174:177], v[182:185], v[110:113]
	v_mfma_f32_16x16x32_bf16 v[102:105], v[166:169], v[196:199], v[102:105]
	v_mfma_f32_16x16x32_bf16 v[94:97], v[174:177], v[196:199], v[94:97]
	v_mfma_f32_16x16x32_bf16 v[86:89], v[166:169], v[204:207], v[86:89]
	v_mfma_f32_16x16x32_bf16 v[78:81], v[174:177], v[204:207], v[78:81]
	v_mfma_f32_16x16x32_bf16 v[70:73], v[166:169], v[212:215], v[70:73]
	v_mfma_f32_16x16x32_bf16 v[66:69], v[174:177], v[212:215], v[66:69]
	s_barrier
	s_setprio 0
	s_add_i32 s0, s0, s39
	v_lshl_add_u64 v[140:141], v[140:141], 0, s[84:85]
	s_mov_b32 m0, s0
	ds_read_b128 v[178:181], v145 offset:49152
	ds_read_b128 v[182:185], v145 offset:50176
	ds_read_b128 v[192:195], v145 offset:51200
	ds_read_b128 v[196:199], v145 offset:52224
	ds_read_b128 v[200:203], v145 offset:53248
	ds_read_b128 v[204:207], v145 offset:54272
	ds_read_b128 v[208:211], v145 offset:55296
	ds_read_b128 v[212:215], v145 offset:56320
	global_load_lds_dwordx4 v[140:141], off
	s_add_i32 m0, s0, 0x2000
	s_add_u32 s28, s28, 0x80080
	v_lshl_add_u64 v[140:141], v[188:189], 0, s[84:85]
	s_addc_u32 s29, s29, 0
	s_add_i32 s0, s1, s39
	global_load_lds_dwordx4 v[140:141], off
	v_lshl_add_u64 v[140:141], s[28:29], 0, v[186:187]
	s_mov_b32 m0, s0
	s_nop 0
	global_load_lds_dwordx4 v[140:141], off
	v_lshl_add_u64 v[140:141], s[28:29], 0, v[130:131]
	s_add_i32 m0, s0, 0x2000
	s_nop 0
	global_load_lds_dwordx4 v[140:141], off
	v_lshl_add_u64 v[140:141], v[216:217], 0, s[84:85]
	s_mov_b32 m0, s43
	s_nop 0
	global_load_lds_dwordx4 v[140:141], off
	v_lshl_add_u64 v[140:141], v[218:219], 0, s[84:85]
	s_mov_b32 m0, s44
	s_nop 0
	global_load_lds_dwordx4 v[140:141], off
	s_waitcnt vmcnt(8)
	s_waitcnt lgkmcnt(0)
	s_setprio 2
	s_barrier

	v_mfma_f32_16x16x32_bf16 v[62:65], v[146:149], v[178:181], v[62:65]
	v_mfma_f32_16x16x32_bf16 v[58:61], v[154:157], v[178:181], v[58:61]
	v_mfma_f32_16x16x32_bf16 v[50:53], v[146:149], v[192:195], v[50:53]
	v_mfma_f32_16x16x32_bf16 v[42:45], v[154:157], v[192:195], v[42:45]
	v_mfma_f32_16x16x32_bf16 v[34:37], v[146:149], v[200:203], v[34:37]
	v_mfma_f32_16x16x32_bf16 v[26:29], v[154:157], v[200:203], v[26:29]
	v_mfma_f32_16x16x32_bf16 v[18:21], v[146:149], v[208:211], v[18:21]
	v_mfma_f32_16x16x32_bf16 v[10:13], v[154:157], v[208:211], v[10:13]
	v_mfma_f32_16x16x32_bf16 v[62:65], v[150:153], v[182:185], v[62:65]
	v_mfma_f32_16x16x32_bf16 v[58:61], v[158:161], v[182:185], v[58:61]
	v_mfma_f32_16x16x32_bf16 v[50:53], v[150:153], v[196:199], v[50:53]
	v_mfma_f32_16x16x32_bf16 v[42:45], v[158:161], v[196:199], v[42:45]
	v_mfma_f32_16x16x32_bf16 v[34:37], v[150:153], v[204:207], v[34:37]
	v_mfma_f32_16x16x32_bf16 v[26:29], v[158:161], v[204:207], v[26:29]
	v_mfma_f32_16x16x32_bf16 v[18:21], v[150:153], v[212:215], v[18:21]
	v_mfma_f32_16x16x32_bf16 v[10:13], v[158:161], v[212:215], v[10:13]


	v_mfma_f32_16x16x32_bf16 v[54:57], v[162:165], v[178:181], v[54:57]
	v_mfma_f32_16x16x32_bf16 v[46:49], v[170:173], v[178:181], v[46:49]
	v_mfma_f32_16x16x32_bf16 v[38:41], v[162:165], v[192:195], v[38:41]
	v_mfma_f32_16x16x32_bf16 v[30:33], v[170:173], v[192:195], v[30:33]
	v_mfma_f32_16x16x32_bf16 v[22:25], v[162:165], v[200:203], v[22:25]
	v_mfma_f32_16x16x32_bf16 v[14:17], v[170:173], v[200:203], v[14:17]
	v_mfma_f32_16x16x32_bf16 v[6:9], v[162:165], v[208:211], v[6:9]
	v_mfma_f32_16x16x32_bf16 v[2:5], v[170:173], v[208:211], v[2:5]
	v_mfma_f32_16x16x32_bf16 v[54:57], v[166:169], v[182:185], v[54:57]
	v_mfma_f32_16x16x32_bf16 v[46:49], v[174:177], v[182:185], v[46:49]
	v_mfma_f32_16x16x32_bf16 v[38:41], v[166:169], v[196:199], v[38:41]
	v_mfma_f32_16x16x32_bf16 v[30:33], v[174:177], v[196:199], v[30:33]
	v_mfma_f32_16x16x32_bf16 v[22:25], v[166:169], v[204:207], v[22:25]
	v_mfma_f32_16x16x32_bf16 v[14:17], v[174:177], v[204:207], v[14:17]
	v_mfma_f32_16x16x32_bf16 v[6:9], v[166:169], v[212:215], v[6:9]
	v_mfma_f32_16x16x32_bf16 v[2:5], v[174:177], v[212:215], v[2:5]
	s_barrier
	s_setprio 0
	s_add_i32 s55, s55, 2
	s_add_u32 s26, s26, 0x100
	s_addc_u32 s27, s27, 0
	s_add_u32 s53, s53, 0x100
	s_addc_u32 s54, s54, 0
	s_cmp_gt_u32 s55, 29
	s_cbranch_scc0 .LBB0_443
	s_and_b64 vcc, exec, s[14:15]
	s_cbranch_vccz .LBB0_446
	s_barrier

.LBB0_1126:
	s_add_u32 s0, s28, 0xfff80080
	s_addc_u32 s1, s29, -1
	s_add_i32 s54, 0, 0x10000
	s_cmp_eq_u32 s53, 28
	s_cselect_b32 s35, s19, s1
	s_cselect_b32 s34, s25, s0
	s_cselect_b32 s31, s17, s52
	s_cselect_b32 s30, s27, s51
	s_add_i32 s55, 0, 0x14000
	v_add_u32_e32 v126, s54, v237
	v_add_u32_e32 v158, s55, v237
	ds_read_b128 v[90:93], v126
	ds_read_b128 v[102:105], v126 offset:1024
	ds_read_b128 v[114:117], v126 offset:2048
	ds_read_b128 v[126:129], v126 offset:3072
	ds_read_b128 v[138:141], v158
	ds_read_b128 v[142:145], v158 offset:1024
	ds_read_b128 v[154:157], v158 offset:2048
	ds_read_b128 v[158:161], v158 offset:3072
	v_lshl_add_u64 v[188:189], s[28:29], 0, v[198:199]
	s_add_i32 m0, s40, 0xc000
	ds_read_b128 v[162:165], v238
	ds_read_b128 v[166:169], v238 offset:1024
	ds_read_b128 v[170:173], v238 offset:2048
	ds_read_b128 v[174:177], v238 offset:3072
	ds_read_b128 v[178:181], v238 offset:4096
	ds_read_b128 v[182:185], v238 offset:5120
	ds_read_b128 v[202:205], v238 offset:6144
	ds_read_b128 v[206:209], v238 offset:7168
	global_load_lds_dwordx4 v[188:189], off
	v_lshl_add_u64 v[188:189], s[28:29], 0, v[200:201]
	s_add_i32 m0, s40, 0xe000
	s_nop 0
	global_load_lds_dwordx4 v[188:189], off
	s_waitcnt vmcnt(8)
	s_waitcnt lgkmcnt(0)
	s_setprio 2
	s_barrier

	v_mfma_f32_16x16x32_bf16 v[150:153], v[90:93], v[162:165], v[150:153]
	v_mfma_f32_16x16x32_bf16 v[146:149], v[114:117], v[162:165], v[146:149]
	v_mfma_f32_16x16x32_bf16 v[122:125], v[90:93], v[170:173], v[122:125]
	v_mfma_f32_16x16x32_bf16 v[118:121], v[114:117], v[170:173], v[118:121]
	v_mfma_f32_16x16x32_bf16 v[98:101], v[90:93], v[178:181], v[98:101]
	v_mfma_f32_16x16x32_bf16 v[94:97], v[114:117], v[178:181], v[94:97]
	v_mfma_f32_16x16x32_bf16 v[78:81], v[90:93], v[202:205], v[78:81]
	v_mfma_f32_16x16x32_bf16 v[74:77], v[114:117], v[202:205], v[74:77]
	v_mfma_f32_16x16x32_bf16 v[150:153], v[102:105], v[166:169], v[150:153]
	v_mfma_f32_16x16x32_bf16 v[146:149], v[126:129], v[166:169], v[146:149]
	v_mfma_f32_16x16x32_bf16 v[122:125], v[102:105], v[174:177], v[122:125]
	v_mfma_f32_16x16x32_bf16 v[118:121], v[126:129], v[174:177], v[118:121]
	v_mfma_f32_16x16x32_bf16 v[98:101], v[102:105], v[182:185], v[98:101]
	v_mfma_f32_16x16x32_bf16 v[94:97], v[126:129], v[182:185], v[94:97]
	v_mfma_f32_16x16x32_bf16 v[78:81], v[102:105], v[206:209], v[78:81]
	v_mfma_f32_16x16x32_bf16 v[74:77], v[126:129], v[206:209], v[74:77]


	v_mfma_f32_16x16x32_bf16 v[134:137], v[138:141], v[162:165], v[134:137]
	v_mfma_f32_16x16x32_bf16 v[130:133], v[154:157], v[162:165], v[130:133]
	v_mfma_f32_16x16x32_bf16 v[110:113], v[138:141], v[170:173], v[110:113]
	v_mfma_f32_16x16x32_bf16 v[106:109], v[154:157], v[170:173], v[106:109]
	v_mfma_f32_16x16x32_bf16 v[86:89], v[138:141], v[178:181], v[86:89]
	v_mfma_f32_16x16x32_bf16 v[82:85], v[154:157], v[178:181], v[82:85]
	v_mfma_f32_16x16x32_bf16 v[70:73], v[138:141], v[202:205], v[70:73]
	v_mfma_f32_16x16x32_bf16 v[66:69], v[154:157], v[202:205], v[66:69]
	v_mfma_f32_16x16x32_bf16 v[134:137], v[142:145], v[166:169], v[134:137]
	v_mfma_f32_16x16x32_bf16 v[130:133], v[158:161], v[166:169], v[130:133]
	v_mfma_f32_16x16x32_bf16 v[110:113], v[142:145], v[174:177], v[110:113]
	v_mfma_f32_16x16x32_bf16 v[106:109], v[158:161], v[174:177], v[106:109]
	v_mfma_f32_16x16x32_bf16 v[86:89], v[142:145], v[182:185], v[86:89]
	v_mfma_f32_16x16x32_bf16 v[82:85], v[158:161], v[182:185], v[82:85]
	v_mfma_f32_16x16x32_bf16 v[70:73], v[142:145], v[206:209], v[70:73]
	v_mfma_f32_16x16x32_bf16 v[66:69], v[158:161], v[206:209], v[66:69]
	s_barrier
	s_setprio 0
	s_add_i32 s0, s54, s39
	v_lshl_add_u64 v[188:189], s[30:31], 0, v[186:187]
	s_mov_b32 m0, s0
	ds_read_b128 v[162:165], v238 offset:16384
	ds_read_b128 v[166:169], v238 offset:17408
	ds_read_b128 v[170:173], v238 offset:18432
	ds_read_b128 v[174:177], v238 offset:19456
	ds_read_b128 v[178:181], v238 offset:20480
	ds_read_b128 v[182:185], v238 offset:21504
	ds_read_b128 v[202:205], v238 offset:22528
	ds_read_b128 v[206:209], v238 offset:23552
	global_load_lds_dwordx4 v[188:189], off
	s_add_i32 m0, s0, 0x2000
	s_add_u32 s0, s30, 0x80000
	v_lshl_add_u64 v[210:211], s[30:31], 0, v[196:197]
	s_addc_u32 s1, s31, 0
	s_add_i32 s54, s55, s39
	global_load_lds_dwordx4 v[210:211], off
	v_lshl_add_u64 v[212:213], s[0:1], 0, v[186:187]
	s_mov_b32 m0, s54
	v_lshl_add_u64 v[214:215], s[34:35], 0, v[194:195]
	global_load_lds_dwordx4 v[212:213], off
	v_lshl_add_u64 v[212:213], s[0:1], 0, v[196:197]
	s_add_i32 m0, s54, 0x2000
	s_nop 0
	global_load_lds_dwordx4 v[212:213], off
	v_lshl_add_u64 v[212:213], s[34:35], 0, v[192:193]
	s_mov_b32 m0, s40
	s_nop 0
	global_load_lds_dwordx4 v[212:213], off
	s_mov_b32 m0, s41
	s_nop 0
	global_load_lds_dwordx4 v[214:215], off
	s_waitcnt vmcnt(8)
	s_waitcnt lgkmcnt(0)
	s_setprio 2
	s_barrier

	v_mfma_f32_16x16x32_bf16 v[62:65], v[90:93], v[162:165], v[62:65]
	v_mfma_f32_16x16x32_bf16 v[58:61], v[114:117], v[162:165], v[58:61]
	v_mfma_f32_16x16x32_bf16 v[46:49], v[90:93], v[170:173], v[46:49]
	v_mfma_f32_16x16x32_bf16 v[42:45], v[114:117], v[170:173], v[42:45]
	v_mfma_f32_16x16x32_bf16 v[30:33], v[90:93], v[178:181], v[30:33]
	v_mfma_f32_16x16x32_bf16 v[26:29], v[114:117], v[178:181], v[26:29]
	v_mfma_f32_16x16x32_bf16 v[14:17], v[90:93], v[202:205], v[14:17]
	v_mfma_f32_16x16x32_bf16 v[10:13], v[114:117], v[202:205], v[10:13]
	v_mfma_f32_16x16x32_bf16 v[62:65], v[102:105], v[166:169], v[62:65]
	v_mfma_f32_16x16x32_bf16 v[58:61], v[126:129], v[166:169], v[58:61]
	v_mfma_f32_16x16x32_bf16 v[46:49], v[102:105], v[174:177], v[46:49]
	v_mfma_f32_16x16x32_bf16 v[42:45], v[126:129], v[174:177], v[42:45]
	v_mfma_f32_16x16x32_bf16 v[30:33], v[102:105], v[182:185], v[30:33]
	v_mfma_f32_16x16x32_bf16 v[26:29], v[126:129], v[182:185], v[26:29]
	v_mfma_f32_16x16x32_bf16 v[14:17], v[102:105], v[206:209], v[14:17]
	v_mfma_f32_16x16x32_bf16 v[10:13], v[126:129], v[206:209], v[10:13]


	v_mfma_f32_16x16x32_bf16 v[54:57], v[138:141], v[162:165], v[54:57]
	v_mfma_f32_16x16x32_bf16 v[50:53], v[154:157], v[162:165], v[50:53]
	v_mfma_f32_16x16x32_bf16 v[38:41], v[138:141], v[170:173], v[38:41]
	v_mfma_f32_16x16x32_bf16 v[34:37], v[154:157], v[170:173], v[34:37]
	v_mfma_f32_16x16x32_bf16 v[22:25], v[138:141], v[178:181], v[22:25]
	v_mfma_f32_16x16x32_bf16 v[18:21], v[154:157], v[178:181], v[18:21]
	v_mfma_f32_16x16x32_bf16 v[6:9], v[138:141], v[202:205], v[6:9]
	v_mfma_f32_16x16x32_bf16 v[2:5], v[154:157], v[202:205], v[2:5]
	v_mfma_f32_16x16x32_bf16 v[54:57], v[142:145], v[166:169], v[54:57]
	v_mfma_f32_16x16x32_bf16 v[50:53], v[158:161], v[166:169], v[50:53]
	v_mfma_f32_16x16x32_bf16 v[38:41], v[142:145], v[174:177], v[38:41]
	v_mfma_f32_16x16x32_bf16 v[34:37], v[158:161], v[174:177], v[34:37]
	v_mfma_f32_16x16x32_bf16 v[22:25], v[142:145], v[182:185], v[22:25]
	v_mfma_f32_16x16x32_bf16 v[18:21], v[158:161], v[182:185], v[18:21]
	v_mfma_f32_16x16x32_bf16 v[6:9], v[142:145], v[206:209], v[6:9]
	v_mfma_f32_16x16x32_bf16 v[2:5], v[158:161], v[206:209], v[2:5]
	s_barrier
	s_setprio 0
	s_add_i32 s54, 0, 0x18000
	s_add_i32 s55, 0, 0x1c000
	v_add_u32_e32 v126, s54, v237
	v_add_u32_e32 v158, s55, v237
	ds_read_b128 v[90:93], v126
	ds_read_b128 v[102:105], v126 offset:1024
	ds_read_b128 v[114:117], v126 offset:2048
	ds_read_b128 v[126:129], v126 offset:3072
	ds_read_b128 v[138:141], v158
	ds_read_b128 v[142:145], v158 offset:1024
	ds_read_b128 v[154:157], v158 offset:2048
	ds_read_b128 v[158:161], v158 offset:3072
	s_add_u32 s0, s34, 0x80000
	s_addc_u32 s1, s35, 0
	s_mov_b32 m0, s42
	v_lshl_add_u64 v[216:217], s[0:1], 0, v[192:193]
	ds_read_b128 v[162:165], v238 offset:32768
	ds_read_b128 v[166:169], v238 offset:33792
	ds_read_b128 v[170:173], v238 offset:34816
	ds_read_b128 v[174:177], v238 offset:35840
	ds_read_b128 v[178:181], v238 offset:36864
	ds_read_b128 v[182:185], v238 offset:37888
	ds_read_b128 v[202:205], v238 offset:38912
	ds_read_b128 v[206:209], v238 offset:39936
	global_load_lds_dwordx4 v[216:217], off
	v_lshl_add_u64 v[216:217], s[0:1], 0, v[194:195]
	s_mov_b32 m0, s43
	s_nop 0
	global_load_lds_dwordx4 v[216:217], off
	s_waitcnt vmcnt(8)
	s_waitcnt lgkmcnt(0)
	s_setprio 2
	s_barrier

	v_mfma_f32_16x16x32_bf16 v[150:153], v[90:93], v[162:165], v[150:153]
	v_mfma_f32_16x16x32_bf16 v[146:149], v[114:117], v[162:165], v[146:149]
	v_mfma_f32_16x16x32_bf16 v[122:125], v[90:93], v[170:173], v[122:125]
	v_mfma_f32_16x16x32_bf16 v[118:121], v[114:117], v[170:173], v[118:121]
	v_mfma_f32_16x16x32_bf16 v[98:101], v[90:93], v[178:181], v[98:101]
	v_mfma_f32_16x16x32_bf16 v[94:97], v[114:117], v[178:181], v[94:97]
	v_mfma_f32_16x16x32_bf16 v[78:81], v[90:93], v[202:205], v[78:81]
	v_mfma_f32_16x16x32_bf16 v[74:77], v[114:117], v[202:205], v[74:77]
	v_mfma_f32_16x16x32_bf16 v[150:153], v[102:105], v[166:169], v[150:153]
	v_mfma_f32_16x16x32_bf16 v[146:149], v[126:129], v[166:169], v[146:149]
	v_mfma_f32_16x16x32_bf16 v[122:125], v[102:105], v[174:177], v[122:125]
	v_mfma_f32_16x16x32_bf16 v[118:121], v[126:129], v[174:177], v[118:121]
	v_mfma_f32_16x16x32_bf16 v[98:101], v[102:105], v[182:185], v[98:101]
	v_mfma_f32_16x16x32_bf16 v[94:97], v[126:129], v[182:185], v[94:97]
	v_mfma_f32_16x16x32_bf16 v[78:81], v[102:105], v[206:209], v[78:81]
	v_mfma_f32_16x16x32_bf16 v[74:77], v[126:129], v[206:209], v[74:77]


	v_mfma_f32_16x16x32_bf16 v[134:137], v[138:141], v[162:165], v[134:137]
	v_mfma_f32_16x16x32_bf16 v[130:133], v[154:157], v[162:165], v[130:133]
	v_mfma_f32_16x16x32_bf16 v[110:113], v[138:141], v[170:173], v[110:113]
	v_mfma_f32_16x16x32_bf16 v[106:109], v[154:157], v[170:173], v[106:109]
	v_mfma_f32_16x16x32_bf16 v[86:89], v[138:141], v[178:181], v[86:89]
	v_mfma_f32_16x16x32_bf16 v[82:85], v[154:157], v[178:181], v[82:85]
	v_mfma_f32_16x16x32_bf16 v[70:73], v[138:141], v[202:205], v[70:73]
	v_mfma_f32_16x16x32_bf16 v[66:69], v[154:157], v[202:205], v[66:69]
	v_mfma_f32_16x16x32_bf16 v[134:137], v[142:145], v[166:169], v[134:137]
	v_mfma_f32_16x16x32_bf16 v[130:133], v[158:161], v[166:169], v[130:133]
	v_mfma_f32_16x16x32_bf16 v[110:113], v[142:145], v[174:177], v[110:113]
	v_mfma_f32_16x16x32_bf16 v[106:109], v[158:161], v[174:177], v[106:109]
	v_mfma_f32_16x16x32_bf16 v[86:89], v[142:145], v[182:185], v[86:89]
	v_mfma_f32_16x16x32_bf16 v[82:85], v[158:161], v[182:185], v[82:85]
	v_mfma_f32_16x16x32_bf16 v[70:73], v[142:145], v[206:209], v[70:73]
	v_mfma_f32_16x16x32_bf16 v[66:69], v[158:161], v[206:209], v[66:69]
	s_barrier
	s_setprio 0
	s_add_i32 s0, s54, s39
	v_lshl_add_u64 v[188:189], v[188:189], 0, s[84:85]
	s_mov_b32 m0, s0
	ds_read_b128 v[162:165], v238 offset:49152
	ds_read_b128 v[166:169], v238 offset:50176
	ds_read_b128 v[170:173], v238 offset:51200
	ds_read_b128 v[174:177], v238 offset:52224
	ds_read_b128 v[178:181], v238 offset:53248
	ds_read_b128 v[182:185], v238 offset:54272
	ds_read_b128 v[202:205], v238 offset:55296
	ds_read_b128 v[206:209], v238 offset:56320
	global_load_lds_dwordx4 v[188:189], off
	s_add_i32 m0, s0, 0x2000
	s_add_u32 s0, s30, 0x80080
	v_lshl_add_u64 v[188:189], v[210:211], 0, s[84:85]
	s_addc_u32 s1, s31, 0
	s_add_i32 s30, s55, s39
	global_load_lds_dwordx4 v[188:189], off
	v_lshl_add_u64 v[188:189], s[0:1], 0, v[186:187]
	s_mov_b32 m0, s30
	s_nop 0
	global_load_lds_dwordx4 v[188:189], off
	v_lshl_add_u64 v[188:189], s[0:1], 0, v[196:197]
	s_add_i32 m0, s30, 0x2000
	s_nop 0
	global_load_lds_dwordx4 v[188:189], off
	v_lshl_add_u64 v[188:189], v[212:213], 0, s[84:85]
	s_mov_b32 m0, s47
	s_nop 0
	global_load_lds_dwordx4 v[188:189], off
	v_lshl_add_u64 v[188:189], v[214:215], 0, s[84:85]
	s_mov_b32 m0, s48
	s_nop 0
	global_load_lds_dwordx4 v[188:189], off
	s_waitcnt vmcnt(8)
	s_waitcnt lgkmcnt(0)
	s_setprio 2
	s_barrier

	v_mfma_f32_16x16x32_bf16 v[62:65], v[90:93], v[162:165], v[62:65]
	v_mfma_f32_16x16x32_bf16 v[58:61], v[114:117], v[162:165], v[58:61]
	v_mfma_f32_16x16x32_bf16 v[46:49], v[90:93], v[170:173], v[46:49]
	v_mfma_f32_16x16x32_bf16 v[42:45], v[114:117], v[170:173], v[42:45]
	v_mfma_f32_16x16x32_bf16 v[30:33], v[90:93], v[178:181], v[30:33]
	v_mfma_f32_16x16x32_bf16 v[26:29], v[114:117], v[178:181], v[26:29]
	v_mfma_f32_16x16x32_bf16 v[14:17], v[90:93], v[202:205], v[14:17]
	v_mfma_f32_16x16x32_bf16 v[10:13], v[114:117], v[202:205], v[10:13]
	v_mfma_f32_16x16x32_bf16 v[62:65], v[102:105], v[166:169], v[62:65]
	v_mfma_f32_16x16x32_bf16 v[58:61], v[126:129], v[166:169], v[58:61]
	v_mfma_f32_16x16x32_bf16 v[46:49], v[102:105], v[174:177], v[46:49]
	v_mfma_f32_16x16x32_bf16 v[42:45], v[126:129], v[174:177], v[42:45]
	v_mfma_f32_16x16x32_bf16 v[30:33], v[102:105], v[182:185], v[30:33]
	v_mfma_f32_16x16x32_bf16 v[26:29], v[126:129], v[182:185], v[26:29]
	v_mfma_f32_16x16x32_bf16 v[14:17], v[102:105], v[206:209], v[14:17]
	v_mfma_f32_16x16x32_bf16 v[10:13], v[126:129], v[206:209], v[10:13]


	v_mfma_f32_16x16x32_bf16 v[54:57], v[138:141], v[162:165], v[54:57]
	v_mfma_f32_16x16x32_bf16 v[50:53], v[154:157], v[162:165], v[50:53]
	v_mfma_f32_16x16x32_bf16 v[38:41], v[138:141], v[170:173], v[38:41]
	v_mfma_f32_16x16x32_bf16 v[34:37], v[154:157], v[170:173], v[34:37]
	v_mfma_f32_16x16x32_bf16 v[22:25], v[138:141], v[178:181], v[22:25]
	v_mfma_f32_16x16x32_bf16 v[18:21], v[154:157], v[178:181], v[18:21]
	v_mfma_f32_16x16x32_bf16 v[6:9], v[138:141], v[202:205], v[6:9]
	v_mfma_f32_16x16x32_bf16 v[2:5], v[154:157], v[202:205], v[2:5]
	v_mfma_f32_16x16x32_bf16 v[54:57], v[142:145], v[166:169], v[54:57]
	v_mfma_f32_16x16x32_bf16 v[50:53], v[158:161], v[166:169], v[50:53]
	v_mfma_f32_16x16x32_bf16 v[38:41], v[142:145], v[174:177], v[38:41]
	v_mfma_f32_16x16x32_bf16 v[34:37], v[158:161], v[174:177], v[34:37]
	v_mfma_f32_16x16x32_bf16 v[22:25], v[142:145], v[182:185], v[22:25]
	v_mfma_f32_16x16x32_bf16 v[18:21], v[158:161], v[182:185], v[18:21]
	v_mfma_f32_16x16x32_bf16 v[6:9], v[142:145], v[206:209], v[6:9]
	v_mfma_f32_16x16x32_bf16 v[2:5], v[158:161], v[206:209], v[2:5]
	s_barrier
	s_setprio 0
	s_add_i32 s53, s53, 2
	s_add_u32 s28, s28, 0x100
	s_addc_u32 s29, s29, 0
	s_add_u32 s51, s51, 0x100
	s_addc_u32 s52, s52, 0
	s_cmp_gt_u32 s53, 29
	s_cbranch_scc0 .LBB0_1126
	s_and_b64 vcc, exec, s[14:15]
	s_cbranch_vccz .LBB0_1129
	s_barrier
